# static s_setprio 1 for waves 0-3 across the P4 unit loop (priority-raise lever, other half)
# baseline (speedup 1.0000x reference)
.LBB0_405:
	s_or_b64 exec, exec, s[0:1]
	s_add_i32 s86, 0, 0x27090
	s_cmp_lg_u32 s86, -1
	s_cselect_b32 s0, s86, 0
	s_cselect_b32 s1, s5, 0
	v_mov_b32_e32 v2, s0
	v_mov_b32_e32 v3, s1
	s_waitcnt lgkmcnt(0)
	s_barrier
	flat_load_dword v1, v[2:3] sc0 sc1
	s_waitcnt vmcnt(0) lgkmcnt(0)
	v_readfirstlane_b32 s36, v1
	s_cmpk_gt_i32 s36, 0x803
	s_cbranch_scc1 .LBB0_799
	s_add_u32 s50, s18, 0x6300000
	s_addc_u32 s51, s19, 0
	s_add_u32 s0, s18, 0xe700000
	s_addc_u32 s1, s19, 0
	v_writelane_b32 v250, s0, 44
	v_ashrrev_i32_e32 v1, 6, v0
	v_and_b32_e32 v185, 3, v1
	v_writelane_b32 v250, s1, 45
	s_add_u32 s0, s18, 0xeb20000
	s_addc_u32 s1, s19, 0
	v_writelane_b32 v250, s0, 46
	v_lshlrev_b32_e32 v2, 10, v185
	v_and_b32_e32 v184, 63, v0
	v_writelane_b32 v250, s1, 47
	s_add_u32 s0, s18, 0x10d28000
	s_addc_u32 s1, s19, 0
	v_writelane_b32 v250, s0, 48
	v_lshlrev_b32_e32 v3, 3, v0
	v_and_b32_e32 v192, 0xffffffc0, v0
	v_writelane_b32 v250, s1, 49
	s_add_u32 s0, s18, 0x14f28000
	s_addc_u32 s1, s19, 0
	v_writelane_b32 v250, s0, 50
	s_add_i32 s17, 0, 0x23000
	v_lshlrev_b32_e32 v190, 3, v1
	v_writelane_b32 v250, s1, 51
	v_cmp_gt_u32_e64 s[0:1], 64, v0
	v_lshl_add_u32 v191, v1, 12, s17
	v_and_b32_e32 v3, 0xfffff800, v3
	v_writelane_b32 v250, s0, 36
	v_lshl_add_u32 v187, v185, 12, s17
	v_readlane_b32 s6, v251, 52
	v_writelane_b32 v250, s1, 37
	s_movk_i32 s1, 0x100
	v_readlane_b32 s0, v250, 20
	v_cmp_gt_u32_e64 s[40:41], s1, v0
	v_and_b32_e32 v0, 0xffffff00, v0
	v_add_u32_e32 v186, s0, v2
	s_mov_b32 s0, 0x8400
	v_mad_u32_u24 v189, v185, s0, 0
	s_movk_i32 s0, 0x4400
	v_mul_lo_u32 v1, v1, s0
	v_cmp_eq_u32_e64 s[0:1], s1, v0
	v_add_u32_e32 v193, 0, v1
	v_readlane_b32 s10, v251, 55
	v_writelane_b32 v250, s0, 52
	v_readlane_b32 s12, v251, 57
	v_add_u32_e32 v188, v187, v3
	v_writelane_b32 v250, s1, 53
	s_add_u32 s0, s18, 0x6300004
	v_writelane_b32 v250, s0, 54
	s_addc_u32 s0, s19, 0
	v_writelane_b32 v250, s0, 55
	s_add_u32 s0, s18, 0x6300008
	v_writelane_b32 v250, s0, 56
	s_addc_u32 s0, s19, 0
	v_writelane_b32 v250, s0, 57
	s_add_u32 s0, s18, 0x630000c
	v_writelane_b32 v250, s0, 58
	s_addc_u32 s0, s19, 0
	v_writelane_b32 v250, s0, 59
	v_add_u32_e32 v194, 0x11000, v193
	v_readlane_b32 s0, v250, 21
	v_readlane_b32 s7, v251, 53
	v_readlane_b32 s4, v251, 54
	v_add_u32_e32 v195, s0, v2
	v_readlane_b32 s11, v251, 56
	v_readlane_b32 s13, v251, 58
	v_readlane_b32 s14, v250, 2
	s_cmp_lg_u64 s[40:41], 0
	s_cbranch_scc0 .Lp4prio_skip
	s_setprio 1
